# v29: conv_run loops get a distance-2 software prefetch (8 dword touches at +512B after the real loads), loop-top wait vmcnt(12)
# baseline (speedup 1.0000x reference)
.LBB0_163:
	s_or_b64 exec, exec, s[0:1]
	s_or_b32 s34, s33, 7
	s_add_u32 s12, s82, 0x6400000
	s_addc_u32 s13, s83, 0
	s_add_u32 s14, s82, 0x6200000
	v_and_b32_e32 v39, 31, v0
	v_lshrrev_b32_e32 v163, 5, v0
	v_and_b32_e32 v41, 0x80, v0
	s_addc_u32 s15, s83, 0
	v_lshl_add_u32 v40, v39, 10, 0
	v_cmp_eq_u32_e64 s[0:1], 0, v41
	v_bitop3_b32 v41, v163, v0, 31 bitop3:0x78
	s_add_u32 s18, s82, 0x4200000
	v_lshl_add_u32 v50, v41, 2, v40
	v_bitop3_b32 v41, v163, v39, 16 bitop3:0x36
	s_addc_u32 s19, s83, 0
	v_lshl_add_u32 v49, v41, 2, v40
	v_bitop3_b32 v41, v163, v39, 32 bitop3:0x36
	v_bitop3_b32 v39, v163, v39, 48 bitop3:0x36
	v_readlane_b32 s36, v254, 46
	s_add_u32 s20, s82, 0x2200000
	v_lshlrev_b32_e32 v162, 4, v0
	s_movk_i32 s3, 0xf0
	v_lshl_add_u32 v48, v41, 2, v40
	v_lshl_add_u32 v39, v39, 2, v40
	v_or_b32_e32 v40, 32, v1
	v_readlane_b32 s50, v254, 60
	v_readlane_b32 s51, v254, 61
	s_addc_u32 s21, s83, 0
	v_lshl_add_u32 v44, v40, 8, 0
	v_bitop3_b32 v45, v40, s3, v162 bitop3:0x48
	v_or_b32_e32 v40, 64, v1
	s_cmp_eq_u64 s[50:51], 0
	v_lshl_add_u32 v47, v40, 8, 0
	v_bitop3_b32 v51, v40, s3, v162 bitop3:0x48
	v_or_b32_e32 v40, 0x60, v1
	s_cselect_b64 s[22:23], -1, 0
	s_add_u32 s24, s82, 0x1a00000
	v_readlane_b32 s10, v254, 3
	v_lshlrev_b32_e32 v37, 3, v0
	v_bitop3_b32 v43, v1, s3, v162 bitop3:0x48
	v_bitop3_b32 v55, v40, s3, v162 bitop3:0x48
	s_addc_u32 s25, s83, 0
	s_lshl_b32 s3, s10, 10
	v_and_b32_e32 v38, 0x78, v37
	v_mov_b32_e32 v37, 0
	s_or_b32 s35, s3, 0x80
	s_lshl_b32 s3, s10, 6
	v_and_b32_e32 v164, 64, v0
	v_lshl_add_u32 v42, v1, 8, 0
	v_lshl_add_u32 v54, v40, 8, 0
	v_lshlrev_b32_e32 v40, 2, v46
	v_mov_b32_e32 v41, v37
	v_readlane_b32 s37, v254, 47
	v_readlane_b32 s38, v254, 48
	s_or_b32 s36, s3, 8
	s_lshl_b32 s3, s10, 4
	s_mov_b32 s11, 0
	v_cmp_eq_u32_e64 s[4:5], 0, v164
	v_lshl_add_u64 v[40:41], s[50:51], 0, v[40:41]
	s_or_b32 s37, s3, 2
	v_add_u32_e32 v53, v42, v43
	v_add_u32_e32 v52, v44, v45
	v_add_u32_e32 v51, v47, v51
	v_add_u32_e32 v47, v54, v55
	s_mov_b32 s38, 0
	v_readlane_b32 s39, v254, 49
	v_readlane_b32 s40, v254, 50
	v_readlane_b32 s41, v254, 51
	v_readlane_b32 s42, v254, 52
	v_readlane_b32 s43, v254, 53
	v_readlane_b32 s44, v254, 54
	v_readlane_b32 s45, v254, 55
	v_readlane_b32 s46, v254, 56
	v_readlane_b32 s47, v254, 57
	v_readlane_b32 s48, v254, 58
	v_readlane_b32 s49, v254, 59
	s_waitcnt vmcnt(0)
.LBB0_164:
	s_waitcnt vmcnt(12)
	v_mov_b64_e32 v[72:73], v[2:3]
	v_mov_b64_e32 v[74:75], v[4:5]
	v_mov_b64_e32 v[76:77], v[6:7]
	v_mov_b64_e32 v[78:79], v[8:9]
	v_mov_b64_e32 v[80:81], v[10:11]
	v_mov_b64_e32 v[82:83], v[12:13]
	v_mov_b64_e32 v[84:85], v[14:15]
	v_mov_b64_e32 v[86:87], v[16:17]
	v_mov_b64_e32 v[88:89], v[18:19]
	v_mov_b64_e32 v[90:91], v[20:21]
	v_mov_b64_e32 v[92:93], v[22:23]
	v_mov_b64_e32 v[94:95], v[24:25]
	v_mov_b64_e32 v[96:97], v[26:27]
	v_mov_b64_e32 v[98:99], v[28:29]
	v_mov_b64_e32 v[100:101], v[30:31]
	v_mov_b64_e32 v[102:103], v[32:33]
	v_mov_b64_e32 v[104:105], v[64:65]
	v_mov_b64_e32 v[106:107], v[66:67]
	v_mov_b64_e32 v[108:109], v[68:69]
	v_mov_b64_e32 v[110:111], v[70:71]
	s_add_i32 s10, s33, s38
	s_add_i32 s99, s10, 2
	s_and_b32 s98, s99, 15
	s_cselect_b32 s98, 1, 0
	s_cmp_le_i32 s99, s34
	s_cselect_b32 s98, s98, 0
	s_cmp_ge_i32 s10, s34
	s_cbranch_scc1 .LBB0_189
	s_cmpk_gt_i32 s10, 0xfe
	s_mov_b64 s[30:31], -1
	s_cbranch_scc0 .LBB0_178
	s_cmpk_gt_u32 s10, 0x4fe
	s_mov_b64 s[28:29], -1
	s_cbranch_scc0 .LBB0_176
	s_cmpk_gt_u32 s10, 0x8fe
	s_cbranch_scc0 .LBB0_173
	s_and_b32 s3, s35, 0x780
	s_cmpk_gt_u32 s10, 0x91e
	v_or_b32_e32 v4, s3, v1
	s_mov_b64 s[26:27], -1
	s_cbranch_scc0 .LBB0_170
	s_and_b32 s10, s36, 0xffffff80
	v_lshlrev_b32_e32 v2, 12, v4
	v_mov_b32_e32 v3, v37
	s_addk_i32 s10, 0xb700
	v_lshl_add_u64 v[2:3], s[12:13], 0, v[2:3]
	v_lshl_add_u64 v[2:3], s[10:11], 1, v[2:3]
	v_lshlrev_b32_e32 v6, 1, v38
	v_mov_b32_e32 v7, v37
	v_lshl_add_u64 v[42:43], v[2:3], 0, v[6:7]
	v_or_b32_e32 v2, s10, v46
	v_mov_b32_e32 v3, v37
	v_lshlrev_b64 v[2:3], 13, v[2:3]
	v_lshl_add_u64 v[2:3], s[76:77], 0, v[2:3]
	s_lshl_b32 s10, s3, 2
	v_lshl_add_u64 v[2:3], v[2:3], 0, s[10:11]
	s_mov_b64 s[26:27], 0

.LBB0_180:
	v_lshl_add_u64 v[2:3], v[2:3], 0, v[36:37]
	v_lshl_add_u64 v[10:11], s[28:29], 2, v[2:3]
	v_mov_b64_e32 v[120:121], v[2:3]
	global_load_dwordx4 v[2:5], v[2:3], off
	s_nop 0
	global_load_dwordx4 v[6:9], v[10:11], off
	v_mov_b32_e32 v64, 1.0
	v_mov_b32_e32 v65, 1.0
	v_mov_b32_e32 v66, 1.0
	v_mov_b32_e32 v67, 1.0
	v_mov_b32_e32 v68, 1.0
	v_mov_b32_e32 v69, 1.0
	v_mov_b32_e32 v70, 1.0
	v_mov_b32_e32 v71, 1.0
	v_cmp_ne_u64_e32 vcc, 0, v[44:45]
	s_and_saveexec_b64 s[30:31], vcc
	s_cbranch_execz .LBB0_182
	global_load_dwordx2 v[64:65], v[44:45], off

.LBB0_186:
	s_or_b64 exec, exec, s[30:31]
	v_lshl_add_u64 v[26:27], v[26:27], 0, s[10:11]
	v_lshl_add_u64 v[30:31], v[26:27], 0, s[28:29]
	global_load_dwordx4 v[26:29], v[26:27], off
	s_nop 0
	global_load_dwordx4 v[30:33], v[30:31], off
	s_cmp_lg_u32 s98, 0
	s_cbranch_scc0 .Lpf_hb_same
	global_load_dword v136, v[120:121], off offset:512
	v_lshl_add_u64 v[120:121], v[120:121], 0, s[28:29]
	global_load_dword v136, v[120:121], off offset:512
	v_lshl_add_u64 v[120:121], v[120:121], 0, s[10:11]
	global_load_dword v136, v[120:121], off offset:512
	v_lshl_add_u64 v[120:121], v[120:121], 0, s[28:29]
	global_load_dword v136, v[120:121], off offset:512
	v_lshl_add_u64 v[120:121], v[120:121], 0, s[10:11]
	global_load_dword v136, v[120:121], off offset:512
	v_lshl_add_u64 v[120:121], v[120:121], 0, s[28:29]
	global_load_dword v136, v[120:121], off offset:512
	v_lshl_add_u64 v[120:121], v[120:121], 0, s[10:11]
	global_load_dword v136, v[120:121], off offset:512
	v_lshl_add_u64 v[120:121], v[120:121], 0, s[28:29]
	global_load_dword v136, v[120:121], off offset:512
	s_branch .Lpf_hb_done
.Lpf_hb_same:
	global_load_dword v136, v[120:121], off
	v_lshl_add_u64 v[120:121], v[120:121], 0, s[28:29]
	global_load_dword v136, v[120:121], off
	v_lshl_add_u64 v[120:121], v[120:121], 0, s[10:11]
	global_load_dword v136, v[120:121], off
	v_lshl_add_u64 v[120:121], v[120:121], 0, s[28:29]
	global_load_dword v136, v[120:121], off
	v_lshl_add_u64 v[120:121], v[120:121], 0, s[10:11]
	global_load_dword v136, v[120:121], off
	v_lshl_add_u64 v[120:121], v[120:121], 0, s[28:29]
	global_load_dword v136, v[120:121], off
	v_lshl_add_u64 v[120:121], v[120:121], 0, s[10:11]
	global_load_dword v136, v[120:121], off
	v_lshl_add_u64 v[120:121], v[120:121], 0, s[28:29]
	global_load_dword v136, v[120:121], off
.Lpf_hb_done:
	s_and_saveexec_b64 s[28:29], vcc
	s_cbranch_execz .LBB0_188
	global_load_dwordx2 v[70:71], v[44:45], off offset:384

.LBB0_406:
	s_or_b64 exec, exec, s[0:1]
	s_add_u32 s10, s82, 0x6400000
	s_addc_u32 s11, s83, 0
	v_and_b32_e32 v38, 31, v0
	s_add_u32 s12, s82, 0x6200000
	v_lshl_add_u32 v40, v38, 10, 0
	v_bitop3_b32 v38, v163, v38, 32 bitop3:0x36
	s_addc_u32 s13, s83, 0
	v_lshl_add_u32 v48, v38, 2, v40
	v_add_u32_e32 v38, 48, v163
	s_add_u32 s14, s82, 0x4200000
	v_bitop3_b32 v38, v38, v0, 31 bitop3:0x78
	s_addc_u32 s15, s83, 0
	s_movk_i32 s8, 0xf0
	v_lshl_add_u32 v49, v38, 2, v40
	v_add_u32_e32 v38, 32, v1
	v_readlane_b32 s48, v254, 46
	s_add_u32 s18, s82, 0x2200000
	v_lshl_add_u32 v45, v38, 8, 0
	v_bitop3_b32 v51, v38, s8, v162 bitop3:0x48
	v_or_b32_e32 v38, 64, v1
	v_readlane_b32 s62, v254, 60
	v_readlane_b32 s63, v254, 61
	s_addc_u32 s19, s83, 0
	v_and_b32_e32 v41, 0x80, v0
	v_lshl_add_u32 v52, v38, 8, 0
	v_bitop3_b32 v53, v38, s8, v162 bitop3:0x48
	v_add_u32_e32 v38, 0x60, v1
	s_cmp_eq_u64 s[62:63], 0
	v_readlane_b32 s24, v254, 3
	v_cmp_eq_u32_e64 s[4:5], 0, v41
	v_bitop3_b32 v44, v1, s8, v162 bitop3:0x48
	v_bitop3_b32 v41, v163, v0, 31 bitop3:0x78
	v_bitop3_b32 v55, v38, s8, v162 bitop3:0x48
	s_cselect_b64 s[20:21], -1, 0
	s_add_u32 s22, s82, 0x1a00000
	s_mul_i32 s8, s24, 0xc8
	v_and_b32_e32 v37, 62, v1
	v_lshl_add_u32 v46, v41, 2, v40
	v_add_u32_e32 v41, 16, v163
	s_addc_u32 s23, s83, 0
	s_add_i32 s31, s8, 0xffff8908
	s_mul_i32 s8, s24, 0xc80
	v_lshlrev_b32_e32 v36, 3, v0
	v_mov_b32_e32 v39, 0
	v_and_b32_e32 v42, 0x7c, v161
	v_lshl_add_u32 v43, v1, 8, 0
	v_bitop3_b32 v41, v41, v0, 31 bitop3:0x78
	v_lshl_add_u32 v54, v38, 8, 0
	v_lshlrev_b32_e32 v38, 2, v37
	s_add_i32 s33, s8, 0xfff89080
	s_mul_i32 s8, s24, 50
	s_mov_b32 s9, 0
	v_and_b32_e32 v36, 0x78, v36
	v_cmp_eq_u32_e64 s[0:1], 0, v164
	v_lshl_add_u32 v47, v41, 2, v40
	v_lshl_add_u64 v[40:41], s[62:63], 0, v[38:39]
	s_add_i32 s34, s8, 0xffffe242
	v_lshlrev_b32_e32 v38, 2, v42
	v_add_u32_e32 v50, v43, v44
	v_add_u32_e32 v51, v45, v51
	v_add_u32_e32 v52, v52, v53
	v_add_u32_e32 v53, v54, v55
	v_mov_b64_e32 v[42:43], v[34:35]
	v_readlane_b32 s49, v254, 47
	v_readlane_b32 s50, v254, 48
	v_readlane_b32 s51, v254, 49
	v_readlane_b32 s52, v254, 50
	v_readlane_b32 s53, v254, 51
	v_readlane_b32 s54, v254, 52
	v_readlane_b32 s55, v254, 53
	v_readlane_b32 s56, v254, 54
	v_readlane_b32 s57, v254, 55
	v_readlane_b32 s58, v254, 56
	v_readlane_b32 s59, v254, 57
	v_readlane_b32 s60, v254, 58
	v_readlane_b32 s61, v254, 59
	s_waitcnt vmcnt(0)
	s_branch .LBB0_409

.LBB0_409:
	s_waitcnt vmcnt(12)
	v_mov_b64_e32 v[72:73], v[2:3]
	v_mov_b64_e32 v[74:75], v[4:5]
	v_mov_b64_e32 v[76:77], v[6:7]
	v_mov_b64_e32 v[78:79], v[8:9]
	v_mov_b64_e32 v[80:81], v[10:11]
	v_mov_b64_e32 v[82:83], v[12:13]
	v_mov_b64_e32 v[84:85], v[14:15]
	v_mov_b64_e32 v[86:87], v[16:17]
	v_mov_b64_e32 v[88:89], v[18:19]
	v_mov_b64_e32 v[90:91], v[20:21]
	v_mov_b64_e32 v[92:93], v[22:23]
	v_mov_b64_e32 v[94:95], v[24:25]
	v_mov_b64_e32 v[96:97], v[26:27]
	v_mov_b64_e32 v[98:99], v[28:29]
	v_mov_b64_e32 v[100:101], v[30:31]
	v_mov_b64_e32 v[102:103], v[32:33]
	s_add_i32 s35, s3, 1
	s_add_i32 s99, s35, 1
	s_and_b32 s98, s99, 15
	s_cselect_b32 s98, 1, 0
	s_cmp_lt_i32 s99, s30
	s_cselect_b32 s98, s98, 0
	s_cmp_ge_i32 s35, s30
	s_cselect_b64 s[24:25], -1, 0
	s_and_b64 vcc, exec, s[24:25]
	s_mov_b32 s36, s2
	s_cbranch_vccnz .Lcvt_la
	s_cmpk_gt_i32 s3, 0xfe
	s_mov_b64 s[28:29], -1
	s_cbranch_scc0 .LBB0_423
	s_cmpk_gt_u32 s35, 0x4ff
	s_mov_b64 s[26:27], -1
	s_cbranch_scc0 .LBB0_421
	s_cmpk_gt_u32 s35, 0x8ff
	s_cbranch_scc0 .LBB0_418
	s_and_b32 s3, s33, 0x780
	s_cmpk_gt_u32 s35, 0x91f
	v_or_b32_e32 v4, s3, v1
	s_cbranch_scc0 .LBB0_415
	s_and_b32 s8, s31, 0xffffff80
	v_lshlrev_b32_e32 v2, 12, v4
	v_mov_b32_e32 v3, v39
	s_addk_i32 s8, 0xb700
	v_lshl_add_u64 v[2:3], s[10:11], 0, v[2:3]
	v_lshl_add_u64 v[2:3], s[8:9], 1, v[2:3]
	v_lshlrev_b32_e32 v6, 1, v36
	v_mov_b32_e32 v7, v39
	v_lshl_add_u64 v[42:43], v[2:3], 0, v[6:7]
	v_or_b32_e32 v2, s8, v37
	v_mov_b32_e32 v3, v39
	v_lshlrev_b64 v[2:3], 13, v[2:3]
	v_lshl_add_u64 v[2:3], s[76:77], 0, v[2:3]
	s_lshl_b32 s8, s3, 2
	v_lshl_add_u64 v[2:3], v[2:3], 0, s[8:9]
	s_mov_b64 s[26:27], 0

.LBB0_425:
	v_lshl_add_u64 v[2:3], v[2:3], 0, v[38:39]
	v_lshl_add_u64 v[10:11], s[26:27], 2, v[2:3]
	v_mov_b64_e32 v[120:121], v[2:3]
	global_load_dwordx4 v[2:5], v[2:3], off
	s_nop 0
	global_load_dwordx4 v[6:9], v[10:11], off
	v_cmp_ne_u64_e32 vcc, 0, v[44:45]
	s_and_saveexec_b64 s[28:29], vcc
	s_cbranch_execz .LBB0_427
	global_load_dwordx2 v[12:13], v[44:45], off
	s_waitcnt vmcnt(0)
	v_pk_mul_f32 v[4:5], v[4:5], v[12:13] op_sel_hi:[1,0]
	v_pk_mul_f32 v[2:3], v[2:3], v[12:13] op_sel_hi:[1,0]
	v_pk_mul_f32 v[8:9], v[8:9], v[12:13] op_sel:[0,1]
	v_pk_mul_f32 v[6:7], v[6:7], v[12:13] op_sel:[0,1]

.LBB0_431:
	s_or_b64 exec, exec, s[28:29]
	v_lshl_add_u64 v[26:27], v[26:27], 0, s[8:9]
	v_lshl_add_u64 v[30:31], v[26:27], 0, s[26:27]
	global_load_dwordx4 v[26:29], v[26:27], off
	s_nop 0
	global_load_dwordx4 v[30:33], v[30:31], off
	s_cmp_lg_u32 s98, 0
	s_cbranch_scc0 .Lpf_la_same
	global_load_dword v136, v[120:121], off offset:512
	v_lshl_add_u64 v[120:121], v[120:121], 0, s[26:27]
	global_load_dword v136, v[120:121], off offset:512
	v_lshl_add_u64 v[120:121], v[120:121], 0, s[8:9]
	global_load_dword v136, v[120:121], off offset:512
	v_lshl_add_u64 v[120:121], v[120:121], 0, s[26:27]
	global_load_dword v136, v[120:121], off offset:512
	v_lshl_add_u64 v[120:121], v[120:121], 0, s[8:9]
	global_load_dword v136, v[120:121], off offset:512
	v_lshl_add_u64 v[120:121], v[120:121], 0, s[26:27]
	global_load_dword v136, v[120:121], off offset:512
	v_lshl_add_u64 v[120:121], v[120:121], 0, s[8:9]
	global_load_dword v136, v[120:121], off offset:512
	v_lshl_add_u64 v[120:121], v[120:121], 0, s[26:27]
	global_load_dword v136, v[120:121], off offset:512
	s_branch .Lpf_la_done
.Lpf_la_same:
	global_load_dword v136, v[120:121], off
	v_lshl_add_u64 v[120:121], v[120:121], 0, s[26:27]
	global_load_dword v136, v[120:121], off
	v_lshl_add_u64 v[120:121], v[120:121], 0, s[8:9]
	global_load_dword v136, v[120:121], off
	v_lshl_add_u64 v[120:121], v[120:121], 0, s[26:27]
	global_load_dword v136, v[120:121], off
	v_lshl_add_u64 v[120:121], v[120:121], 0, s[8:9]
	global_load_dword v136, v[120:121], off
	v_lshl_add_u64 v[120:121], v[120:121], 0, s[26:27]
	global_load_dword v136, v[120:121], off
	v_lshl_add_u64 v[120:121], v[120:121], 0, s[8:9]
	global_load_dword v136, v[120:121], off
	v_lshl_add_u64 v[120:121], v[120:121], 0, s[26:27]
	global_load_dword v136, v[120:121], off
.Lpf_la_done:
	s_and_saveexec_b64 s[26:27], vcc
	s_cbranch_execz .LBB0_407
	global_load_dwordx2 v[44:45], v[44:45], off offset:384
	s_waitcnt vmcnt(0)
	v_pk_mul_f32 v[28:29], v[28:29], v[44:45] op_sel_hi:[1,0]
	v_pk_mul_f32 v[26:27], v[26:27], v[44:45] op_sel_hi:[1,0]
	v_pk_mul_f32 v[32:33], v[32:33], v[44:45] op_sel:[0,1]
	v_pk_mul_f32 v[30:31], v[30:31], v[44:45] op_sel:[0,1]
	s_branch .LBB0_407

.LBB0_456:
	s_or_b64 exec, exec, s[0:1]
	s_or_b32 s29, s28, 7
	s_add_u32 s8, s82, 0x6400000
	s_addc_u32 s9, s83, 0
	s_add_u32 s10, s82, 0x6200000
	v_and_b32_e32 v39, 31, v0
	v_and_b32_e32 v41, 0x80, v0
	s_addc_u32 s11, s83, 0
	v_lshl_add_u32 v40, v39, 10, 0
	v_cmp_eq_u32_e64 s[0:1], 0, v41
	v_bitop3_b32 v41, v163, v0, 31 bitop3:0x78
	v_bitop3_b32 v39, v163, v39, 32 bitop3:0x36
	s_add_u32 s12, s82, 0x4200000
	v_lshl_add_u32 v50, v41, 2, v40
	v_add_u32_e32 v41, 16, v163
	v_lshl_add_u32 v47, v39, 2, v40
	v_add_u32_e32 v39, 48, v163
	s_addc_u32 s13, s83, 0
	v_bitop3_b32 v41, v41, v0, 31 bitop3:0x78
	v_bitop3_b32 v39, v39, v0, 31 bitop3:0x78
	v_readlane_b32 s48, v254, 46
	s_add_u32 s14, s82, 0x2200000
	s_movk_i32 s3, 0xf0
	v_lshl_add_u32 v49, v41, 2, v40
	v_lshl_add_u32 v39, v39, 2, v40
	v_add_u32_e32 v40, 32, v1
	v_readlane_b32 s62, v254, 60
	v_readlane_b32 s63, v254, 61
	s_addc_u32 s15, s83, 0
	v_lshl_add_u32 v44, v40, 8, 0
	v_bitop3_b32 v45, v40, s3, v162 bitop3:0x48
	v_or_b32_e32 v40, 64, v1
	s_cmp_eq_u64 s[62:63], 0
	v_lshl_add_u32 v46, v40, 8, 0
	v_bitop3_b32 v51, v40, s3, v162 bitop3:0x48
	v_add_u32_e32 v40, 0x60, v1
	s_cselect_b64 s[18:19], -1, 0
	s_add_u32 s20, s82, 0x1a00000
	v_readlane_b32 s6, v254, 3
	v_lshlrev_b32_e32 v37, 3, v0
	v_bitop3_b32 v43, v1, s3, v162 bitop3:0x48
	v_bitop3_b32 v55, v40, s3, v162 bitop3:0x48
	s_addc_u32 s21, s83, 0
	s_lshl_b32 s3, s6, 10
	v_and_b32_e32 v48, 62, v1
	v_and_b32_e32 v38, 0x78, v37
	v_mov_b32_e32 v37, 0
	s_or_b32 s30, s3, 0x80
	s_lshl_b32 s3, s6, 6
	v_lshl_add_u32 v42, v1, 8, 0
	v_lshl_add_u32 v54, v40, 8, 0
	v_lshlrev_b32_e32 v40, 2, v48
	v_mov_b32_e32 v41, v37
	s_or_b32 s31, s3, 8
	s_lshl_b32 s3, s6, 4
	s_mov_b32 s7, 0
	v_cmp_eq_u32_e64 s[4:5], 0, v164
	v_lshl_add_u64 v[40:41], s[62:63], 0, v[40:41]
	s_or_b32 s33, s3, 2
	v_add_u32_e32 v53, v42, v43
	v_add_u32_e32 v52, v44, v45
	v_add_u32_e32 v51, v46, v51
	v_add_u32_e32 v46, v54, v55
	s_mov_b32 s34, 0
	v_readlane_b32 s49, v254, 47
	v_readlane_b32 s50, v254, 48
	v_readlane_b32 s51, v254, 49
	v_readlane_b32 s52, v254, 50
	v_readlane_b32 s53, v254, 51
	v_readlane_b32 s54, v254, 52
	v_readlane_b32 s55, v254, 53
	v_readlane_b32 s56, v254, 54
	v_readlane_b32 s57, v254, 55
	v_readlane_b32 s58, v254, 56
	v_readlane_b32 s59, v254, 57
	v_readlane_b32 s60, v254, 58
	v_readlane_b32 s61, v254, 59
	s_waitcnt vmcnt(0)
.LBB0_457:
	s_waitcnt vmcnt(12)
	v_mov_b64_e32 v[72:73], v[2:3]
	v_mov_b64_e32 v[74:75], v[4:5]
	v_mov_b64_e32 v[76:77], v[6:7]
	v_mov_b64_e32 v[78:79], v[8:9]
	v_mov_b64_e32 v[80:81], v[10:11]
	v_mov_b64_e32 v[82:83], v[12:13]
	v_mov_b64_e32 v[84:85], v[14:15]
	v_mov_b64_e32 v[86:87], v[16:17]
	v_mov_b64_e32 v[88:89], v[18:19]
	v_mov_b64_e32 v[90:91], v[20:21]
	v_mov_b64_e32 v[92:93], v[22:23]
	v_mov_b64_e32 v[94:95], v[24:25]
	v_mov_b64_e32 v[96:97], v[26:27]
	v_mov_b64_e32 v[98:99], v[28:29]
	v_mov_b64_e32 v[100:101], v[30:31]
	v_mov_b64_e32 v[102:103], v[32:33]
	v_mov_b64_e32 v[104:105], v[64:65]
	v_mov_b64_e32 v[106:107], v[66:67]
	v_mov_b64_e32 v[108:109], v[68:69]
	v_mov_b64_e32 v[110:111], v[70:71]
	s_add_i32 s6, s28, s34
	s_add_i32 s99, s6, 2
	s_and_b32 s98, s99, 15
	s_cselect_b32 s98, 1, 0
	s_cmp_le_i32 s99, s29
	s_cselect_b32 s98, s98, 0
	s_cmp_ge_i32 s6, s29
	s_cbranch_scc1 .LBB0_482
	s_cmpk_gt_i32 s6, 0xfe
	s_mov_b64 s[26:27], -1
	s_cbranch_scc0 .LBB0_471
	s_cmpk_gt_u32 s6, 0x4fe
	s_mov_b64 s[24:25], -1
	s_cbranch_scc0 .LBB0_469
	s_cmpk_gt_u32 s6, 0x8fe
	s_cbranch_scc0 .LBB0_466
	s_and_b32 s3, s30, 0x780
	s_cmpk_gt_u32 s6, 0x91e
	v_or_b32_e32 v4, s3, v1
	s_mov_b64 s[22:23], -1
	s_cbranch_scc0 .LBB0_463
	s_and_b32 s6, s31, 0xffffff80
	v_lshlrev_b32_e32 v2, 12, v4
	v_mov_b32_e32 v3, v37
	s_addk_i32 s6, 0xb700
	v_lshl_add_u64 v[2:3], s[8:9], 0, v[2:3]
	v_lshl_add_u64 v[2:3], s[6:7], 1, v[2:3]
	v_lshlrev_b32_e32 v6, 1, v38
	v_mov_b32_e32 v7, v37
	v_lshl_add_u64 v[42:43], v[2:3], 0, v[6:7]
	v_or_b32_e32 v2, s6, v48
	v_mov_b32_e32 v3, v37
	v_lshlrev_b64 v[2:3], 13, v[2:3]
	v_lshl_add_u64 v[2:3], s[76:77], 0, v[2:3]
	s_lshl_b32 s6, s3, 2
	v_lshl_add_u64 v[2:3], v[2:3], 0, s[6:7]
	s_mov_b64 s[22:23], 0

.LBB0_473:
	v_lshl_add_u64 v[2:3], v[2:3], 0, v[36:37]
	v_lshl_add_u64 v[10:11], s[24:25], 2, v[2:3]
	v_mov_b64_e32 v[120:121], v[2:3]
	global_load_dwordx4 v[2:5], v[2:3], off
	s_nop 0
	global_load_dwordx4 v[6:9], v[10:11], off
	v_mov_b32_e32 v64, 1.0
	v_mov_b32_e32 v65, 1.0
	v_mov_b32_e32 v66, 1.0
	v_mov_b32_e32 v67, 1.0
	v_mov_b32_e32 v68, 1.0
	v_mov_b32_e32 v69, 1.0
	v_mov_b32_e32 v70, 1.0
	v_mov_b32_e32 v71, 1.0
	v_cmp_ne_u64_e32 vcc, 0, v[44:45]
	s_and_saveexec_b64 s[26:27], vcc
	s_cbranch_execz .LBB0_475
	global_load_dwordx2 v[64:65], v[44:45], off

.LBB0_479:
	s_or_b64 exec, exec, s[26:27]
	v_lshl_add_u64 v[26:27], v[26:27], 0, s[6:7]
	v_lshl_add_u64 v[30:31], v[26:27], 0, s[24:25]
	global_load_dwordx4 v[26:29], v[26:27], off
	s_nop 0
	global_load_dwordx4 v[30:33], v[30:31], off
	s_cmp_lg_u32 s98, 0
	s_cbranch_scc0 .Lpf_ha_same
	global_load_dword v136, v[120:121], off offset:512
	v_lshl_add_u64 v[120:121], v[120:121], 0, s[24:25]
	global_load_dword v136, v[120:121], off offset:512
	v_lshl_add_u64 v[120:121], v[120:121], 0, s[6:7]
	global_load_dword v136, v[120:121], off offset:512
	v_lshl_add_u64 v[120:121], v[120:121], 0, s[24:25]
	global_load_dword v136, v[120:121], off offset:512
	v_lshl_add_u64 v[120:121], v[120:121], 0, s[6:7]
	global_load_dword v136, v[120:121], off offset:512
	v_lshl_add_u64 v[120:121], v[120:121], 0, s[24:25]
	global_load_dword v136, v[120:121], off offset:512
	v_lshl_add_u64 v[120:121], v[120:121], 0, s[6:7]
	global_load_dword v136, v[120:121], off offset:512
	v_lshl_add_u64 v[120:121], v[120:121], 0, s[24:25]
	global_load_dword v136, v[120:121], off offset:512
	s_branch .Lpf_ha_done
.Lpf_ha_same:
	global_load_dword v136, v[120:121], off
	v_lshl_add_u64 v[120:121], v[120:121], 0, s[24:25]
	global_load_dword v136, v[120:121], off
	v_lshl_add_u64 v[120:121], v[120:121], 0, s[6:7]
	global_load_dword v136, v[120:121], off
	v_lshl_add_u64 v[120:121], v[120:121], 0, s[24:25]
	global_load_dword v136, v[120:121], off
	v_lshl_add_u64 v[120:121], v[120:121], 0, s[6:7]
	global_load_dword v136, v[120:121], off
	v_lshl_add_u64 v[120:121], v[120:121], 0, s[24:25]
	global_load_dword v136, v[120:121], off
	v_lshl_add_u64 v[120:121], v[120:121], 0, s[6:7]
	global_load_dword v136, v[120:121], off
	v_lshl_add_u64 v[120:121], v[120:121], 0, s[24:25]
	global_load_dword v136, v[120:121], off
.Lpf_ha_done:
	s_and_saveexec_b64 s[24:25], vcc
	s_cbranch_execz .LBB0_481
	global_load_dwordx2 v[70:71], v[44:45], off offset:384
